# code placement: three 4-byte pads so that all four GEMM K-loop heads (and the GDN chunk loop) start at 0 mod 8 bytes as in the baseline
# speedup vs baseline: 1.0066x; 1.0066x over previous
;     __device__ __forceinline__ bool next(int i, int& pm, int& pn, int& k0, int& nk, int& split) const {
;         const int L = i * G + c;
;         if (L >= nwg) {
;             if (!tail || L >= nwg + 256) return false;
;             const int j = L - nwg, t = j >> 2, sp = j & 3;
;             pm = 128 + (t >> 2); pn = t & 3; split = 1 + sp;
;             const int q = (nkt / 4) & ~1, r = (nkt - 4 * q) / 2;
;             k0 = sp * q + 2 * (sp < r ? sp : r); nk = q + (sp < r ? 2 : 0);
;             return true;
;         }
;         k0 = 0; nk = nkt; split = 0;
;         int wgid = L; { const int q = nwg / NXCD, r = nwg % NXCD, xcd = wgid % NXCD, off = wgid / NXCD; wgid = (xcd < r ? xcd * (q + 1) : r * (q + 1) + (xcd - r) * q) + off; }
;         const int nig = WGM * nN, gid = wgid / nig, fm = gid * WGM, gsz = (nM - fm) < WGM ? (nM - fm) : WGM;
;         pm = fm + ((wgid % nig) % gsz); pn = (wgid % nig) / gsz; return true;
; template <class Epi>
; __device__ __forceinline__ void gemm_phase(LAS unsigned char* lds, const Gemm g, const StaticOrder& S, const Epi& E) {
;     ...
;         const bool has_next = S.next(ui + 1, npm, npn, nk0, nnk, nsp);
.Lmy_prio_p2:
	s_nop 0
	s_add_i32 s24, s24, 1
	s_mul_i32 s30, s24, s88
	s_add_i32 s30, s30, s2
	s_cmpk_lt_i32 s30, 0x900
	s_cselect_b64 s[70:71], -1, 0
	s_cmpk_gt_i32 s30, 0x8ff
	s_cselect_b64 s[64:65], -1, 0
	s_and_b64 vcc, exec, s[64:65]
	s_cbranch_vccnz .LBB0_566
	s_ashr_i32 s25, s30, 31
	s_lshr_b32 s25, s25, 29
	s_add_i32 s25, s30, s25
	s_ashr_i32 s31, s25, 3
	s_and_b32 s25, s25, -8
	s_sub_i32 s25, s30, s25
	s_cmp_lt_i32 s25, 0
	s_movk_i32 s8, 0x121
	s_cselect_b32 s30, s8, 0x120
	s_mul_i32 s25, s30, s25
	s_add_i32 s25, s25, s31
	s_ashr_i32 s30, s25, 31
	s_lshr_b32 s30, s30, 25
	s_add_i32 s30, s25, s30
	s_ashr_i32 s31, s30, 7
	s_and_b32 s30, s30, 0xff80
	s_sub_i32 s25, s25, s30
	s_bfe_i32 s30, s25, 0x80000
	s_bfe_u32 s30, s30, 0x3000c
	s_add_i32 s30, s25, s30
	s_bfe_i32 s33, s30, 0x80000
	s_and_b32 s30, s30, 0xf8
	s_sub_i32 s25, s25, s30
	s_lshl_b32 s31, s31, 3
	s_sext_i32_i16 s33, s33
	s_sext_i32_i8 s25, s25
	s_add_i32 s60, s31, s25
	s_ashr_i32 s62, s33, 3
	s_mov_b32 s25, 16

; #define PG8_WAIT_V(n) asm volatile("s_waitcnt vmcnt(" #n ")" ::: "memory")
; #define PG8_BAR __builtin_amdgcn_s_barrier()
; template <class Epi>
; __device__ __forceinline__ void gemm_phase(LAS unsigned char* lds, const Gemm g, const StaticOrder& S, const Epi& E) {
;     ...
;     PG8_WAIT_V(0);
;     if (wr == 0) PG8_BAR;
;     PG8_BAR;
.LBB0_713:
	s_setprio 0
	s_nop 0
	s_waitcnt vmcnt(0)
	s_cmpk_gt_u32 s5, 0xff
	s_cbranch_scc1 .LBB0_715
	s_barrier

;     __device__ __forceinline__ bool next(int i, int& pm, int& pn, int& k0, int& nk, int& split) const {
;         const int L = i * G + c;
;         if (L >= nwg) {
;             if (!tail || L >= nwg + 256) return false;
;             const int j = L - nwg, t = j >> 2, sp = j & 3;
;             pm = 128 + (t >> 2); pn = t & 3; split = 1 + sp;
;             const int q = (nkt / 4) & ~1, r = (nkt - 4 * q) / 2;
;             k0 = sp * q + 2 * (sp < r ? sp : r); nk = q + (sp < r ? 2 : 0);
;             return true;
;         }
;         k0 = 0; nk = nkt; split = 0;
;         int wgid = L; { const int q = nwg / NXCD, r = nwg % NXCD, xcd = wgid % NXCD, off = wgid / NXCD; wgid = (xcd < r ? xcd * (q + 1) : r * (q + 1) + (xcd - r) * q) + off; }
;         const int nig = WGM * nN, gid = wgid / nig, fm = gid * WGM, gsz = (nM - fm) < WGM ? (nM - fm) : WGM;
;         pm = fm + ((wgid % nig) % gsz); pn = (wgid % nig) / gsz; return true;
; template <class Epi>
; __device__ __forceinline__ void gemm_phase(LAS unsigned char* lds, const Gemm g, const StaticOrder& S, const Epi& E) {
;     ...
;         const bool has_next = S.next(ui + 1, npm, npn, nk0, nnk, nsp);
.Lmy_prio_p6:
	s_nop 0
	s_add_i32 s19, s19, 1
	s_mul_i32 s4, s19, s88
	s_add_i32 s4, s4, s2
	s_cmp_lt_i32 s4, s39
	s_cselect_b64 s[62:63], -1, 0
	s_cmp_ge_i32 s4, s39
	s_cselect_b64 s[40:41], -1, 0
	s_and_b64 vcc, exec, s[40:41]
	s_cbranch_vccnz .LBB0_1764
	s_ashr_i32 s5, s4, 31
	s_lshr_b32 s5, s5, 29
	s_add_i32 s5, s4, s5
	s_ashr_i32 s8, s5, 3
	s_and_b32 s5, s5, -8
	s_sub_i32 s4, s4, s5
	s_lshr_b32 s5, s4, 31
	s_or_b32 s5, s5, s65
	s_mul_i32 s4, s5, s4
	s_add_i32 s4, s4, s8
	s_mul_hi_i32 s5, s4, 0x2e8ba2e9
	s_lshr_b32 s8, s5, 31
	s_ashr_i32 s5, s5, 5
	s_add_i32 s5, s5, s8
	s_lshl_b32 s8, s5, 3
	s_sub_i32 s20, s38, s8
	s_min_i32 s20, s20, 8
	s_abs_i32 s21, s20
	v_cvt_f32_u32_e32 v8, s21
	s_sub_i32 s23, 0, s21
	s_mulk_i32 s5, 0xb0
	s_sub_i32 s4, s4, s5
	v_rcp_iflag_f32_e32 v8, v8
	s_abs_i32 s5, s4
	s_xor_b32 s22, s4, s20
	s_ashr_i32 s22, s22, 31
	v_mul_f32_e32 v8, 0x4f7ffffe, v8
	v_cvt_u32_f32_e32 v8, v8
	s_nop 0
	v_readfirstlane_b32 s24, v8
	s_mul_i32 s23, s23, s24
	s_mul_hi_u32 s23, s24, s23
	s_add_i32 s24, s24, s23
	s_mul_hi_u32 s23, s5, s24
	s_mul_i32 s24, s23, s21
	s_sub_i32 s5, s5, s24
	s_add_i32 s25, s23, 1
	s_sub_i32 s24, s5, s21
	s_cmp_ge_u32 s5, s21
	s_cselect_b32 s23, s25, s23
	s_cselect_b32 s5, s24, s5
	s_add_i32 s24, s23, 1
	s_cmp_ge_u32 s5, s21
	s_cselect_b32 s5, s24, s23
	s_xor_b32 s5, s5, s22
	s_sub_i32 s46, s5, s22
	s_mul_i32 s5, s46, s20
	s_sub_i32 s4, s4, s5
	s_add_i32 s44, s4, s8
	s_mov_b32 s20, 16
